# dilated-window work queue: next item index fetched (atomic) one item ahead so its round trip overlaps the current item
# baseline (speedup 1.0000x reference)
.LBB0_436:
	s_or_b64 exec, exec, s[78:79]
	s_add_u32 s12, s18, 0x2000
	s_addc_u32 s13, s19, 0
	s_mov_b64 s[42:43], 0
	s_and_saveexec_b64 s[2:3], s[88:89]
	v_mov_b32_e32 v1, 1
	global_atomic_add v253, v2, v1, s[12:13] sc0
	s_or_b64 exec, exec, s[2:3]
	s_branch .LBB0_439

.LBB0_439:
	s_barrier
	s_and_saveexec_b64 s[2:3], s[88:89]
	s_cbranch_execz .LBB0_443
	s_waitcnt vmcnt(0)
	v_mov_b32_e32 v0, v253
	v_mov_b32_e32 v1, 1
	ds_write_b32 v198, v0
	global_atomic_add v253, v2, v1, s[12:13] sc0
